# grid barrier: the one agent-scope invalidate that the buffer reuse requires (before the q|k|gate GEMM, after the last read of every region that is later overwritten) kept; the seam before attention re
# speedup vs baseline: 1.0090x; 1.0090x over previous
; __device__ __forceinline__ float ex2(float x) { return __builtin_amdgcn_exp2f(x); }
; __device__ __forceinline__ float rcpf_(float x) { return __builtin_amdgcn_rcpf(x); }
; __device__ __forceinline__ int crow(int reg, int h) { return (reg & 3) + 8 * (reg >> 2) + 4 * h; }
; __device__ __forceinline__ void attn_phase(const Ptrs& P, int gw, int NGW, int lane) {
;     const bf16x8* QF = (const bf16x8*)(P.ws + WS_U1); const bf16x8* KF = QF + (size_t)M * AW / 8; const v2u* GF = (const v2u*)(KF + (size_t)M * AW / 8);
;     const bf16x8* VF = (const bf16x8*)(P.ws + WS_VT); bf16* OG = (bf16*)(P.ws + WS_OG);
;     const int r = lane & 31, hh = lane >> 5;
;     for (int u = gw; u < BATCH * AH * (SEQ / 32); u += NGW) {
;         const int qt = u & 127, bhh = u >> 7, b = bhh >> 4, h = bhh & 15;
;         const size_t rowbase = (size_t)b * SEQ;
;         bf16x8 qf[4], kf[4];
;         { const bf16x8* qp = QF + (size_t)(bhh * 128 + qt) * 256 + lane;
; #pragma unroll
;           for (int ks = 0; ks < 4; ++ks) qf[ks] = qp[ks * 64]; }
;         const bf16x8* kbase = KF + (size_t)bhh * 128 * 256 + lane;
;         const bf16x8* vbase = VF + (size_t)bhh * 128 * 256 + lane;
;         bf16x8 k1[4], k2[4], vf[2][2], v1[2][2];
;     ...
; #pragma unroll
;             for (int i = 0; i < 16; ++i) { float ff = rcpf_(1.0f + ex2(sa[i])), bt = 1.0f - ff;
;                 if (diag) { const bool valid = crow(i, hh) < r; bt = valid ? bt : 0.0f; ff = valid ? ff : 1.0f; }
.Lmy_bar_go_4:
.LBB0_634:
	s_or_b64 exec, exec, s[4:5]
	s_waitcnt lgkmcnt(0)
	s_barrier
.LBB0_635:
	s_cmp_lt_i32 s56, 7
	s_cselect_b64 s[4:5], -1, 0
	s_and_b64 s[38:39], s[4:5], s[2:3]
	s_andn2_b64 vcc, exec, s[38:39]
	s_cbranch_vccnz .LBB0_642
	s_cmpk_gt_i32 s60, 0x1fff
	s_cbranch_scc1 .LBB0_642
	s_waitcnt lgkmcnt(0)
	v_lshlrev_b32_e32 v185, 4, v232
	v_lshlrev_b32_e32 v233, 3, v232
	v_and_b32_e32 v234, 31, v232
	v_lshrrev_b32_e32 v235, 5, v232
	v_lshlrev_b32_e32 v236, 2, v235
	v_lshlrev_b32_e32 v238, 4, v235
	v_cmp_lt_u32_e64 s[4:5], v236, v234
	v_or_b32_e32 v237, 1, v236
	v_cmp_lt_u32_e64 s[6:7], v237, v234
	v_or_b32_e32 v237, 2, v236
	v_cmp_lt_u32_e64 s[8:9], v237, v234
	v_or_b32_e32 v237, 3, v236
	v_cmp_lt_u32_e64 s[10:11], v237, v234
	v_or_b32_e32 v237, 8, v236
	v_cmp_lt_u32_e64 s[12:13], v237, v234
	v_or_b32_e32 v237, 9, v236
	v_cmp_lt_u32_e64 s[14:15], v237, v234
	v_or_b32_e32 v237, 10, v236
	v_cmp_lt_u32_e64 s[16:17], v237, v234
	v_or_b32_e32 v237, 11, v236
	v_cmp_lt_u32_e64 s[18:19], v237, v234
	v_or_b32_e32 v237, 16, v236
	v_cmp_lt_u32_e64 s[20:21], v237, v234
	v_or_b32_e32 v237, 17, v236
	v_cmp_lt_u32_e64 s[22:23], v237, v234
	v_or_b32_e32 v237, 18, v236
	v_cmp_lt_u32_e64 s[24:25], v237, v234
	v_or_b32_e32 v237, 19, v236
	v_cmp_lt_u32_e64 s[26:27], v237, v234
	v_or_b32_e32 v237, 24, v236
	v_cmp_lt_u32_e64 s[28:29], v237, v234
	v_or_b32_e32 v237, 25, v236
	v_cmp_lt_u32_e64 s[30:31], v237, v234
	v_or_b32_e32 v237, 26, v236
	v_cmp_lt_u32_e64 s[34:35], v237, v234
	v_or_b32_e32 v237, 27, v236
	v_cmp_lt_u32_e64 s[36:37], v237, v234
	v_cmp_gt_u32_e64 s[2:3], 32, v232
	s_add_u32 s44, s54, 0x3800000
	s_addc_u32 s45, s55, 0
	s_add_u32 s46, s54, 0x5800000
	s_addc_u32 s47, s55, 0
	s_add_u32 s48, s54, 0x9c00000
	s_addc_u32 s49, s55, 0
	s_add_u32 s50, s54, 0x7800000
	s_addc_u32 s51, s55, 0
	s_add_u32 s42, s54, 0xbc00000
	s_addc_u32 s43, s55, 0
	s_mov_b32 s58, s60
	s_cmpk_lg_i32 s64, 0x100
	s_cbranch_scc1 .Lp6_nomap
	s_and_b32 s78, s33, 7
	s_lshl_b32 s78, s78, 8
	s_lshr_b32 s79, s33, 7
	s_lshl_b32 s79, s79, 7
	s_or_b32 s78, s78, s79
	s_bfe_u32 s79, s33, 0x40003
	s_lshl_b32 s79, s79, 3
	s_or_b32 s78, s78, s79
	s_and_b32 s79, s60, 7
	s_or_b32 s58, s78, s79
